# v23 + nt on the attention Q/K/V data loads
# speedup vs baseline: 1.0050x; 1.0025x over previous
; #define LBAR() do { asm volatile("s_waitcnt lgkmcnt(0)" ::: "memory"); __builtin_amdgcn_s_barrier(); asm volatile("" ::: "memory"); } while (0)
; __device__ __forceinline__ void attn_unit(const AtArgs& A, unsigned char* lds, int unit, int tid, int wave, int lane) {
;     ...
;     const int b = unit >> 6, kvh = (unit >> 5) & 1, nb = unit & 31;
;     const int fr = lane & 15, fq = lane >> 4;
;     const float* ROPE = (const float*)(A.ws + WS_ROPE);
;     u32x4 qn0, qn1;
;     const bf16* pq0;
;     {
;         const int g_ = wave >> 1, qh_ = wave & 1, hq_ = kvh * 4 + g_, row = lane >> 2, chunk = lane & 3;
;         const size_t t = (size_t)b * SEQ + nb * 128 + qh_ * 64 + row;
;         pq0 = Q + t * QW + QC_Q + hq_ * 64 + chunk * 16;
;         qn0 = *(const u32x4*)pq0; qn1 = *(const u32x4*)(pq0 + 8);
;     }
;     LBAR();
; #pragma unroll
;     for (int rep = 0; rep < 2; ++rep) {
;         const int task = tid + rep * 512, key = task >> 2, chunk = task & 3;
;         const int s = (nb - 1) * 128 + key; const bool valid = s >= 0;
;         const size_t t = (size_t)b * SEQ + (valid ? s : 0);
;         float x[16];
;         load_norm_rope(Q + t * QW + QC_K + kvh * 64 + chunk * 16, valid, A.kg, chunk, ROPE + t * 16, 1.0f, x);
.LBB0_493:
	s_ashr_i32 s20, s24, 6
	s_and_b32 s3, s24, 31
	s_ashr_i32 s21, s20, 31
	s_lshl_b64 s[0:1], s[20:21], 12
	s_lshl_b32 s2, s3, 7
	s_bfe_u32 s11, s24, 0x10005
	s_or_b32 s12, s0, s2
	s_mov_b32 s13, s1
	s_lshl_b32 s10, s11, 2
	v_lshl_add_u64 v[0:1], v[34:35], 0, s[12:13]
	v_mov_b64_e32 v[2:3], s[60:61]
	s_add_i32 s10, s10, s79
	v_mad_u64_u32 v[2:3], s[12:13], v0, s25, v[2:3]
	v_mad_i32_i24 v3, v1, s25, v3
	s_lshl_b32 s6, s10, 7
	v_lshl_add_u64 v[0:1], v[2:3], 0, s[6:7]
	v_lshlrev_b32_e32 v38, 1, v36
	v_lshl_add_u64 v[50:51], v[0:1], 0, v[38:39]
	global_load_dwordx4 v[8:11], v[50:51], off offset:16 nt
	global_load_dwordx4 v[12:15], v[50:51], off nt
	s_addk_i32 s2, 0xff80
	v_add_u32_e32 v0, s2, v33
	s_waitcnt lgkmcnt(0)
	s_barrier
	v_cmp_lt_i32_e32 vcc, -1, v0
	v_mov_b32_e32 v1, v39
	s_lshl_b32 s11, s11, 6
	v_cndmask_b32_e32 v0, 0, v0, vcc
	v_lshl_add_u64 v[52:53], s[0:1], 0, v[0:1]
	v_mov_b32_e32 v28, v39
	v_mov_b32_e32 v29, v39
	v_mov_b32_e32 v30, v39
	v_mov_b32_e32 v31, v39
	v_mov_b32_e32 v24, v39
	v_mov_b32_e32 v25, v39
	v_mov_b32_e32 v26, v39
	v_mov_b32_e32 v27, v39
	s_and_saveexec_b64 s[16:17], vcc
	s_cbranch_execz .LBB0_495
	v_mov_b64_e32 v[0:1], s[60:61]
	v_mad_u64_u32 v[0:1], s[12:13], v52, s25, v[0:1]
	v_mad_i32_i24 v1, v53, s25, v1
	s_lshl_b32 s6, s11, 1
	v_lshl_add_u64 v[0:1], v[0:1], 0, s[6:7]
	v_lshl_add_u64 v[0:1], v[0:1], 0, v[38:39]
	global_load_dwordx4 v[28:31], v[0:1], off offset:1024 nt
	global_load_dwordx4 v[24:27], v[0:1], off offset:1040 nt

; __device__ __forceinline__ unsigned pk2(float lo, float hi) { f32x2_t v = {lo, hi}; bf16x2_t b = __builtin_convertvector(v, bf16x2_t); return __builtin_bit_cast(unsigned, b); }
; __device__ __forceinline__ void load_norm_rope(const bf16* p, bool valid, const float* __restrict__ gain, int chunk, const float* rp, float scale, float* x) {
;     u32x4 w0 = (u32x4){0, 0, 0, 0}, w1 = w0;
;     if (valid) { w0 = *(const u32x4*)p; w1 = *(const u32x4*)(p + 8); }
;     norm_rope(w0, w1, gain, chunk, rp, scale, x);
; __device__ __forceinline__ void attn_unit(const AtArgs& A, unsigned char* lds, int unit, int tid, int wave, int lane) {
;     ...
;     for (int rep = 0; rep < 2; ++rep) {
;         const int task = tid + rep * 512, key = task >> 2, chunk = task & 3;
;         const int s = (nb - 1) * 128 + key; const bool valid = s >= 0;
;         const size_t t = (size_t)b * SEQ + (valid ? s : 0);
;         float x[16];
;         load_norm_rope(Q + t * QW + QC_K + kvh * 64 + chunk * 16, valid, A.kg, chunk, ROPE + t * 16, 1.0f, x);
;         u32x4 o0, o1; o0.x = pk2(x[0], x[1]); o0.y = pk2(x[2], x[3]); o0.z = pk2(x[4], x[5]); o0.w = pk2(x[6], x[7]); o1.x = pk2(x[8], x[9]); o1.y = pk2(x[10], x[11]); o1.z = pk2(x[12], x[13]); o1.w = pk2(x[14], x[15]);
;         *(u32x4*)(KS + key * KST + chunk * 16) = o0; *(u32x4*)(KS + key * KST + chunk * 16 + 8) = o1;
.LBB0_497:
	s_or_b64 exec, exec, s[16:17]
	v_cvt_pk_bf16_f32 v94, v60, v61
	v_cvt_pk_bf16_f32 v95, v58, v59
	v_cvt_pk_bf16_f32 v96, v56, v57
	v_cvt_pk_bf16_f32 v97, v54, v55
	v_cvt_pk_bf16_f32 v24, v24, v25
	v_cvt_pk_bf16_f32 v25, v26, v27
	v_cvt_pk_bf16_f32 v26, v28, v29
	v_cvt_pk_bf16_f32 v27, v30, v31
	ds_write_b128 v90, v[94:97]
	ds_write_b128 v90, v[24:27] offset:16
	v_add_u32_e32 v25, s2, v37
	v_cmp_lt_i32_e32 vcc, -1, v25
	v_mov_b32_e32 v27, v39
	v_mov_b32_e32 v24, 0
	v_cndmask_b32_e32 v26, 0, v25, vcc
	v_lshl_add_u64 v[52:53], s[0:1], 0, v[26:27]
	v_mov_b32_e32 v25, 0
	v_mov_b32_e32 v26, 0
	v_mov_b32_e32 v27, 0
	v_mov_b32_e32 v28, 0
	v_mov_b32_e32 v29, 0
	v_mov_b32_e32 v30, 0
	v_mov_b32_e32 v31, 0
	s_and_saveexec_b64 s[16:17], vcc
	s_cbranch_execz .LBB0_499
	v_mov_b64_e32 v[24:25], s[60:61]
	v_mad_u64_u32 v[24:25], s[12:13], v52, s25, v[24:25]
	v_mad_i32_i24 v25, v53, s25, v25
	s_lshl_b32 s6, s11, 1
	v_lshl_add_u64 v[24:25], v[24:25], 0, s[6:7]
	v_lshl_add_u64 v[28:29], v[24:25], 0, v[38:39]
	global_load_dwordx4 v[24:27], v[28:29], off offset:1024 nt
	s_nop 0
	global_load_dwordx4 v[28:31], v[28:29], off offset:1040 nt

; __device__ __forceinline__ unsigned pk2(float lo, float hi) { f32x2_t v = {lo, hi}; bf16x2_t b = __builtin_convertvector(v, bf16x2_t); return __builtin_bit_cast(unsigned, b); }
; __device__ __forceinline__ void attn_unit(const AtArgs& A, unsigned char* lds, int unit, int tid, int wave, int lane) {
;     ...
;         u32x4 o0, o1; o0.x = pk2(x[0], x[1]); o0.y = pk2(x[2], x[3]); o0.z = pk2(x[4], x[5]); o0.w = pk2(x[6], x[7]); o1.x = pk2(x[8], x[9]); o1.y = pk2(x[10], x[11]); o1.z = pk2(x[12], x[13]); o1.w = pk2(x[14], x[15]);
;         *(u32x4*)(KS + key * KST + chunk * 16) = o0; *(u32x4*)(KS + key * KST + chunk * 16 + 8) = o1;
;     }
; #pragma unroll
;     for (int rep = 0; rep < 4; ++rep) {
;         const int task = tid + rep * 512, key = task >> 3, c8 = task & 7;
;         const int s = (nb - 1) * 128 + key; const bool valid = s >= 0;
;         const size_t t = (size_t)b * SEQ + (valid ? s : 0);
;         u32x4 w = (u32x4){0, 0, 0, 0};
;         if (valid) w = *(const u32x4*)(Q + t * QW + QC_V + kvh * 64 + c8 * 8);
;         const unsigned ww[4] = {w.x, w.y, w.z, w.w};
;         const int pkey = (((key >> 3) ^ c8) << 3) | (key & 7);
; #pragma unroll
;         for (int i = 0; i < 4; ++i) { VT[(c8 * 8 + 2 * i) * VST + pkey] = (bf16)(ww[i] & 0xffffu); VT[(c8 * 8 + 2 * i + 1) * VST + pkey] = (bf16)(ww[i] >> 16); }
;     }
.LBB0_501:
	s_or_b64 exec, exec, s[16:17]
	v_cvt_pk_bf16_f32 v18, v24, v25
	v_cvt_pk_bf16_f32 v19, v22, v23
	v_cvt_pk_bf16_f32 v20, v20, v21
	v_cvt_pk_bf16_f32 v21, v16, v17
	v_cvt_pk_bf16_f32 v4, v4, v5
	v_cvt_pk_bf16_f32 v5, v6, v7
	v_cvt_pk_bf16_f32 v6, v0, v1
	v_add_u32_e32 v38, s2, v43
	v_cvt_pk_bf16_f32 v7, v2, v3
	ds_write_b128 v91, v[18:21]
	ds_write_b128 v91, v[4:7] offset:16
	v_cmp_lt_i32_e32 vcc, -1, v38
	v_mov_b32_e32 v0, 0
	v_lshlrev_b32_e32 v6, 1, v42
	v_mov_b32_e32 v2, 0
	v_mov_b32_e32 v3, 0
	v_mov_b32_e32 v4, 0
	v_mov_b32_e32 v5, 0
	s_and_saveexec_b64 s[16:17], vcc
	s_cbranch_execz .LBB0_503
	v_lshl_add_u64 v[2:3], s[0:1], 0, v[38:39]
	v_mov_b64_e32 v[4:5], s[60:61]
	v_mad_u64_u32 v[4:5], s[12:13], v2, s25, v[4:5]
	v_mad_i32_i24 v5, v3, s25, v5
	s_lshl_b32 s6, s11, 1
	v_lshl_add_u64 v[2:3], v[4:5], 0, s[6:7]
	v_mov_b32_e32 v7, v39
	v_lshl_add_u64 v[2:3], v[2:3], 0, v[6:7]
	global_load_dwordx4 v[2:5], v[2:3], off offset:1280 nt
.LBB0_503:
	s_or_b64 exec, exec, s[16:17]
	v_add_u32_e32 v38, s2, v65
	s_waitcnt vmcnt(0)
	ds_write_b16 v62, v2 offset:36864
	ds_write_b16_d16_hi v63, v2 offset:37552
	ds_write_b16 v62, v3 offset:38240
	ds_write_b16_d16_hi v63, v3 offset:38928
	ds_write_b16 v62, v4 offset:39616
	ds_write_b16_d16_hi v63, v4 offset:40304
	ds_write_b16 v62, v5 offset:40992
	ds_write_b16_d16_hi v63, v5 offset:41680
	v_cmp_lt_i32_e32 vcc, -1, v38
	v_mov_b32_e32 v1, 0
	v_mov_b32_e32 v2, 0
	v_mov_b32_e32 v3, 0
	s_and_saveexec_b64 s[16:17], vcc
	s_cbranch_execz .LBB0_505
	v_lshl_add_u64 v[0:1], s[0:1], 0, v[38:39]
	v_mov_b64_e32 v[2:3], s[60:61]
	v_mad_u64_u32 v[2:3], s[12:13], v0, s25, v[2:3]
	v_mad_i32_i24 v3, v1, s25, v3
	s_lshl_b32 s6, s11, 1
	v_lshl_add_u64 v[0:1], v[2:3], 0, s[6:7]
	v_mov_b32_e32 v7, v39
	v_lshl_add_u64 v[0:1], v[0:1], 0, v[6:7]
	global_load_dwordx4 v[0:3], v[0:1], off offset:1280 nt
.LBB0_505:
	s_or_b64 exec, exec, s[16:17]
	v_add_u32_e32 v38, s2, v68
	s_waitcnt vmcnt(0)
	ds_write_b16 v66, v0 offset:36864
	ds_write_b16_d16_hi v67, v0 offset:37552
	ds_write_b16 v66, v1 offset:38240
	ds_write_b16_d16_hi v67, v1 offset:38928
	ds_write_b16 v66, v2 offset:39616
	ds_write_b16_d16_hi v67, v2 offset:40304
	ds_write_b16 v66, v3 offset:40992
	ds_write_b16_d16_hi v67, v3 offset:41680
	v_cmp_lt_i32_e32 vcc, -1, v38
	v_mov_b32_e32 v0, 0
	v_mov_b32_e32 v2, 0
	v_mov_b32_e32 v3, 0
	v_mov_b32_e32 v4, 0
	v_mov_b32_e32 v5, 0
	s_and_saveexec_b64 s[16:17], vcc
	s_cbranch_execz .LBB0_507
	v_lshl_add_u64 v[2:3], s[0:1], 0, v[38:39]
	v_mov_b64_e32 v[4:5], s[60:61]
	v_mad_u64_u32 v[4:5], s[12:13], v2, s25, v[4:5]
	v_mad_i32_i24 v5, v3, s25, v5
	s_lshl_b32 s6, s11, 1
	v_lshl_add_u64 v[2:3], v[4:5], 0, s[6:7]
	v_mov_b32_e32 v7, v39
	v_lshl_add_u64 v[2:3], v[2:3], 0, v[6:7]
	global_load_dwordx4 v[2:5], v[2:3], off offset:1280 nt
.LBB0_507:
	s_or_b64 exec, exec, s[16:17]
	v_add_u32_e32 v38, s2, v71
	s_waitcnt vmcnt(0)
	ds_write_b16 v69, v2 offset:36864
	ds_write_b16_d16_hi v70, v2 offset:37552
	ds_write_b16 v69, v3 offset:38240
	ds_write_b16_d16_hi v70, v3 offset:38928
	ds_write_b16 v69, v4 offset:39616
	ds_write_b16_d16_hi v70, v4 offset:40304
	ds_write_b16 v69, v5 offset:40992
	ds_write_b16_d16_hi v70, v5 offset:41680
	v_cmp_lt_i32_e32 vcc, -1, v38
	s_mov_b32 s2, 0
	v_mov_b32_e32 v1, 0
	v_mov_b32_e32 v2, 0
	v_mov_b32_e32 v3, 0
	s_and_saveexec_b64 s[16:17], vcc
	s_cbranch_execz .LBB0_509
	v_lshl_add_u64 v[0:1], s[0:1], 0, v[38:39]
	v_mov_b64_e32 v[2:3], s[60:61]
	v_mad_u64_u32 v[2:3], s[12:13], v0, s25, v[2:3]
	v_mad_i32_i24 v3, v1, s25, v3
	s_lshl_b32 s6, s11, 1
	v_lshl_add_u64 v[0:1], v[2:3], 0, s[6:7]
	v_mov_b32_e32 v7, v39
	v_lshl_add_u64 v[0:1], v[0:1], 0, v[6:7]
	global_load_dwordx4 v[0:3], v[0:1], off offset:1280 nt

; __device__ __forceinline__ void norm_rope(u32x4 w0, u32x4 w1, const float* __restrict__ gain, int chunk, const float* rp, float scale, float* x) {
;     const unsigned ww[8] = {w0.x, w0.y, w0.z, w0.w, w1.x, w1.y, w1.z, w1.w};
;     float ss = 0.f;
; #pragma unroll
;     for (int i = 0; i < 8; ++i) { x[2 * i] = __uint_as_float(ww[i] << 16); x[2 * i + 1] = __uint_as_float(ww[i] & 0xffff0000u); ss += x[2 * i] * x[2 * i] + x[2 * i + 1] * x[2 * i + 1]; }
;     ss += dpp_perm<0xB1, 0xF>(ss); ss += dpp_perm<0x4E, 0xF>(ss);
;     const float inv = rsqrtf(ss * (1.0f / 64.0f) + 1e-6f);
; #pragma unroll
;     for (int i = 0; i < 16; ++i) x[i] = x[i] * inv * gain[chunk * 16 + i];
;     if (chunk == 0) rope16(x, rp);
; #pragma unroll
;     for (int i = 0; i < 16; ++i) x[i] *= scale;
; __device__ __forceinline__ void attn_unit(const AtArgs& A, unsigned char* lds, int unit, int tid, int wave, int lane) {
;     ...
;         const int q0 = qh * 64 + st * 16;
;         {
;             const int row = lane >> 2, chunk = lane & 3;
;             const size_t t = (size_t)b * SEQ + nb * 128 + q0 + row;
;             float x[16];
;             const u32x4 qc0 = qn0, qc1 = qn1;
;             { const bf16* pn = pq0 + (size_t)((st < 3) ? st + 1 : 3) * 16 * QW; qn0 = *(const u32x4*)pn; qn1 = *(const u32x4*)(pn + 8); }
;             norm_rope(qc0, qc1, A.qg, chunk, ROPE + t * 16, 0.125f, x);
.LBB0_511:
	s_cmp_lg_u32 s2, 48
	s_cselect_b32 s6, s3, 0x21000
	v_lshl_add_u64 v[4:5], s[6:7], 1, v[50:51]
	global_load_dwordx4 v[0:3], v[4:5], off offset:16 nt
	s_nop 0
	global_load_dwordx4 v[4:7], v[4:5], off nt
	s_nop 0
	global_load_dwordx4 v[16:19], v[44:45], off offset:48
	global_load_dwordx4 v[20:23], v[44:45], off offset:32
	global_load_dwordx4 v[24:27], v[44:45], off offset:16
	global_load_dwordx4 v[28:31], v[44:45], off
	v_and_b32_e32 v59, 0xffff0000, v15
	v_lshlrev_b32_e32 v58, 16, v15
	v_and_b32_e32 v15, 0xffff0000, v14
	v_lshlrev_b32_e32 v14, 16, v14
	v_mov_b32_e32 v96, v59
	v_mov_b32_e32 v97, v15
	v_mov_b32_e32 v60, v58
	v_mov_b32_e32 v61, v14
	v_pk_mul_f32 v[96:97], v[96:97], v[96:97]
	v_and_b32_e32 v57, 0xffff0000, v11
	v_pk_fma_f32 v[60:61], v[60:61], v[60:61], v[96:97]
	v_and_b32_e32 v97, 0xffff0000, v10
	v_lshlrev_b32_e32 v56, 16, v11
	v_lshlrev_b32_e32 v96, 16, v10
	v_mov_b32_e32 v98, v57
	v_mov_b32_e32 v99, v97
	v_mov_b32_e32 v10, v56
	v_mov_b32_e32 v11, v96
	v_pk_mul_f32 v[98:99], v[98:99], v[98:99]
	v_and_b32_e32 v101, 0xffff0000, v9
	v_pk_fma_f32 v[10:11], v[10:11], v[10:11], v[98:99]
	v_and_b32_e32 v99, 0xffff0000, v13
	v_lshlrev_b32_e32 v98, 16, v13
	v_and_b32_e32 v13, 0xffff0000, v12
	v_lshlrev_b32_e32 v12, 16, v12
	v_mov_b32_e32 v108, v13
	v_mov_b32_e32 v109, v99
	v_mov_b32_e32 v102, v12
	v_mov_b32_e32 v103, v98
	v_pk_mul_f32 v[108:109], v[108:109], v[108:109]
	v_lshlrev_b32_e32 v100, 16, v9
	v_pk_fma_f32 v[102:103], v[102:103], v[102:103], v[108:109]
	v_and_b32_e32 v9, 0xffff0000, v8
	v_lshlrev_b32_e32 v8, 16, v8
	v_mov_b32_e32 v110, v101
	v_mov_b32_e32 v111, v9
	v_add_f32_e32 v102, v102, v103
	v_mov_b32_e32 v108, v100
	v_mov_b32_e32 v109, v8
	v_pk_mul_f32 v[110:111], v[110:111], v[110:111]
	v_add_f32_e32 v61, v61, v102
	v_pk_fma_f32 v[108:109], v[108:109], v[108:109], v[110:111]
	v_add_f32_e32 v60, v60, v61
	v_add_f32_e32 v60, v109, v60
	v_add_f32_e32 v60, v108, v60
	v_add_f32_e32 v11, v11, v60
	v_add_f32_e32 v10, v10, v11
	s_nop 1
	v_add_f32_dpp v10, v10, v10 quad_perm:[1,0,3,2] row_mask:0xf bank_mask:0xf bound_ctrl:1
	s_nop 1
	v_add_f32_dpp v10, v10, v10 quad_perm:[2,3,0,1] row_mask:0xf bank_mask:0xf bound_ctrl:1
	v_fmamk_f32 v10, v10, 0x3c800000, v89
	v_cmp_gt_f32_e32 vcc, s34, v10
	v_mul_f32_e32 v11, 0x4b800000, v10
	s_nop 0
	v_cndmask_b32_e32 v10, v10, v11, vcc
	v_rsq_f32_e32 v10, v10
	s_nop 0
	v_mul_f32_e32 v11, 0x45800000, v10
	v_cndmask_b32_e32 v102, v10, v11, vcc
	v_pk_mul_f32 v[10:11], v[102:103], v[12:13] op_sel_hi:[0,1]
	v_pk_mul_f32 v[8:9], v[102:103], v[8:9] op_sel_hi:[0,1]
	s_waitcnt vmcnt(2)
	v_pk_mul_f32 v[8:9], v[20:21], v[8:9]
	s_waitcnt vmcnt(0)
	v_pk_mul_f32 v[60:61], v[28:29], v[10:11]
	v_pk_mul_f32 v[10:11], v[102:103], v[98:99] op_sel_hi:[0,1]
	v_pk_mul_f32 v[28:29], v[30:31], v[10:11]
	v_pk_mul_f32 v[10:11], v[102:103], v[14:15] op_sel_hi:[0,1]
	v_pk_mul_f32 v[24:25], v[24:25], v[10:11]
	v_pk_mul_f32 v[10:11], v[102:103], v[58:59] op_sel_hi:[0,1]
	v_pk_mul_f32 v[14:15], v[102:103], v[96:97] op_sel_hi:[0,1]
	v_pk_mul_f32 v[12:13], v[26:27], v[10:11]
	v_pk_mul_f32 v[10:11], v[102:103], v[100:101] op_sel_hi:[0,1]
	v_pk_mul_f32 v[14:15], v[16:17], v[14:15]
	v_pk_mul_f32 v[16:17], v[102:103], v[56:57] op_sel_hi:[0,1]
	v_pk_mul_f32 v[10:11], v[22:23], v[10:11]
	v_pk_mul_f32 v[16:17], v[16:17], v[18:19]
	s_and_saveexec_b64 s[0:1], s[40:41]
	s_cbranch_execz .LBB0_510
	global_load_dwordx4 v[18:21], v[54:55], off offset:16
	global_load_dwordx4 v[56:59], v[54:55], off offset:-16
	global_load_dwordx4 v[96:99], v[54:55], off
	global_load_dwordx4 v[100:103], v[54:55], off offset:-32
	s_waitcnt vmcnt(1)
	v_pk_mul_f32 v[26:27], v[60:61], v[96:97]
	v_pk_mul_f32 v[22:23], v[8:9], v[96:97]
	s_waitcnt vmcnt(0)
	v_pk_fma_f32 v[8:9], v[8:9], v[100:101], v[26:27]
	v_pk_mul_f32 v[26:27], v[10:11], v[98:99]
	v_pk_fma_f32 v[22:23], v[60:61], v[100:101], v[22:23] neg_lo:[0,0,1] neg_hi:[0,0,1]
	v_pk_fma_f32 v[26:27], v[28:29], v[102:103], v[26:27] neg_lo:[0,0,1] neg_hi:[0,0,1]
	v_pk_mul_f32 v[28:29], v[28:29], v[98:99]
	v_mov_b64_e32 v[60:61], v[22:23]
	v_pk_fma_f32 v[10:11], v[10:11], v[102:103], v[28:29]
	v_pk_mul_f32 v[28:29], v[14:15], v[18:19]
	v_pk_mul_f32 v[18:19], v[24:25], v[18:19]
	v_pk_fma_f32 v[28:29], v[24:25], v[56:57], v[28:29] neg_lo:[0,0,1] neg_hi:[0,0,1]
	v_pk_fma_f32 v[14:15], v[14:15], v[56:57], v[18:19]
	v_pk_mul_f32 v[18:19], v[16:17], v[20:21]
	v_mov_b64_e32 v[24:25], v[28:29]
	v_pk_fma_f32 v[18:19], v[12:13], v[58:59], v[18:19] neg_lo:[0,0,1] neg_hi:[0,0,1]
	v_pk_mul_f32 v[12:13], v[12:13], v[20:21]
	v_mov_b64_e32 v[28:29], v[26:27]
	v_pk_fma_f32 v[16:17], v[16:17], v[58:59], v[12:13]
	v_mov_b64_e32 v[12:13], v[18:19]
	s_branch .LBB0_510
